# P8 small GEMM: fragment reads ordered B,B,A.. with counted lgkmcnt waits so MFMAs start after three reads (on v48)
# baseline (speedup 1.0000x reference)
.LBB0_1290:
	s_waitcnt lgkmcnt(0)
	s_barrier
	ds_read_b128 v[210:213], v145 offset:33792
	ds_read_b128 v[214:217], v145 offset:42240
	ds_read_b128 v[194:197], v145
	ds_read_b128 v[198:201], v145 offset:8448
	ds_read_b128 v[202:205], v145 offset:16896
	ds_read_b128 v[206:209], v145 offset:25344
	s_waitcnt lgkmcnt(3)
	v_mfma_f32_16x16x32_bf16 v[160:163], v[210:213], v[194:197], v[160:163]
	v_mfma_f32_16x16x32_bf16 v[164:167], v[214:217], v[194:197], v[164:167]
	s_waitcnt lgkmcnt(2)
	v_mfma_f32_16x16x32_bf16 v[168:171], v[210:213], v[198:201], v[168:171]
	v_mfma_f32_16x16x32_bf16 v[172:175], v[214:217], v[198:201], v[172:175]
	s_waitcnt lgkmcnt(1)
	v_mfma_f32_16x16x32_bf16 v[176:179], v[210:213], v[202:205], v[176:179]
	v_mfma_f32_16x16x32_bf16 v[180:183], v[214:217], v[202:205], v[180:183]
	s_waitcnt lgkmcnt(0)
	v_mfma_f32_16x16x32_bf16 v[184:187], v[210:213], v[206:209], v[184:187]
	v_mfma_f32_16x16x32_bf16 v[188:191], v[214:217], v[206:209], v[188:191]
	s_add_i32 s8, s8, 2
	v_lshl_add_u64 v[70:71], v[70:71], 0, s[10:11]
	v_lshl_add_u64 v[72:73], v[72:73], 0, s[10:11]
	v_lshl_add_u64 v[62:63], v[62:63], 0, s[10:11]
	v_lshl_add_u64 v[64:65], v[64:65], 0, s[10:11]
	v_lshl_add_u64 v[66:67], v[66:67], 0, s[10:11]
	v_lshl_add_u64 v[68:69], v[68:69], 0, s[10:11]
	s_and_b64 vcc, exec, s[16:17]
	s_cbranch_vccnz .Lsk_p8_reduce

.LBB0_1293:
	s_waitcnt lgkmcnt(0)
	s_barrier
	ds_read_b128 v[210:213], v144 offset:33792
	ds_read_b128 v[214:217], v144 offset:42240
	ds_read_b128 v[194:197], v144
	ds_read_b128 v[198:201], v144 offset:8448
	ds_read_b128 v[202:205], v144 offset:16896
	ds_read_b128 v[206:209], v144 offset:25344
	s_waitcnt lgkmcnt(3)
	v_mfma_f32_16x16x32_bf16 v[160:163], v[210:213], v[194:197], v[160:163]
	v_mfma_f32_16x16x32_bf16 v[164:167], v[214:217], v[194:197], v[164:167]
	s_waitcnt lgkmcnt(2)
	v_mfma_f32_16x16x32_bf16 v[168:171], v[210:213], v[198:201], v[168:171]
	v_mfma_f32_16x16x32_bf16 v[172:175], v[214:217], v[198:201], v[172:175]
	s_waitcnt lgkmcnt(1)
	v_mfma_f32_16x16x32_bf16 v[176:179], v[210:213], v[202:205], v[176:179]
	v_mfma_f32_16x16x32_bf16 v[180:183], v[214:217], v[202:205], v[180:183]
	s_waitcnt lgkmcnt(0)
	v_mfma_f32_16x16x32_bf16 v[184:187], v[210:213], v[206:209], v[184:187]
	v_mfma_f32_16x16x32_bf16 v[188:191], v[214:217], v[206:209], v[188:191]
	v_add_u32_e32 v52, v90, v99
	s_cmp_gt_u32 s8, 12
	s_waitcnt vmcnt(11)
	ds_write_b128 v52, v[4:7]
	v_add_u32_e32 v128, v91, v99
	s_waitcnt vmcnt(10)
	ds_write_b128 v128, v[12:15]
	v_add_u32_e32 v124, v90, v100
	s_waitcnt vmcnt(9)
	ds_write_b128 v124, v[20:23]
	v_add_u32_e32 v124, v91, v100
	s_waitcnt vmcnt(8)
	ds_write_b128 v124, v[28:31]
	s_waitcnt vmcnt(7)
	ds_write_b128 v52, v[36:39] offset:16896
	v_add_u32_e32 v52, v90, v101
	s_waitcnt vmcnt(6)
	ds_write_b128 v52, v[44:47]
	s_cbranch_scc1 .LBB0_1290
	v_add_co_u32_e32 v4, vcc, 0x2c00000, v84
	s_nop 1
	v_addc_co_u32_e32 v5, vcc, 0, v85, vcc
	v_add_co_u32_e32 v12, vcc, 0x1700000, v82
	global_load_dwordx4 v[4:7], v[4:5], off offset:1536
	s_nop 0
	v_addc_co_u32_e32 v13, vcc, 0, v83, vcc
	v_add_co_u32_e32 v20, vcc, 0x2c00000, v80
	global_load_dwordx4 v[12:15], v[12:13], off offset:1536
	s_nop 0
	v_addc_co_u32_e32 v21, vcc, 0, v81, vcc
	v_add_co_u32_e32 v28, vcc, 0x1700000, v78
	global_load_dwordx4 v[20:23], v[20:21], off offset:1536
	s_nop 0
	v_addc_co_u32_e32 v29, vcc, 0, v79, vcc
	v_add_co_u32_e32 v36, vcc, 0x2c00000, v76
	global_load_dwordx4 v[28:31], v[28:29], off offset:1536
	s_nop 0
	v_addc_co_u32_e32 v37, vcc, 0, v77, vcc
	v_add_co_u32_e32 v44, vcc, 0x2c00000, v74
	global_load_dwordx4 v[36:39], v[36:37], off offset:1536
	s_nop 0
	v_addc_co_u32_e32 v45, vcc, 0, v75, vcc
	global_load_dwordx4 v[44:47], v[44:45], off offset:1536
	s_branch .LBB0_1290
